# GEMM prologues: the 6 LDS-DMA loads of K-step 1 issued before the first wait+barrier (vmcnt 2 -> 8) in all 11 gemm instances
# baseline (speedup 1.0000x reference)
; #define PG8_STAGE(bufoff, gbase, voff) do { _Pragma("unroll") for (int _i = 0; _i < 2; ++_i) \
;         __builtin_amdgcn_global_load_lds((const unsigned*)((const char*)(gbase) + (voff)[_i]), (LAS unsigned*)(lds + (bufoff) + ldsw + _i * 8192), 16, 0, 0); } while (0)
; #define PG8_WAIT_V(n) asm volatile("s_waitcnt vmcnt(" #n ")" ::: "memory")
; #define PG8_BAR __builtin_amdgcn_s_barrier()
; template <class Epi, bool ALIGN_EPI>
; __device__ __forceinline__ void gemm_phase(LAS unsigned char* lds, const Gemm g, const StaticOrder& S, const Epi& E) {
;     ...
;     const unsigned ldsw = (unsigned)wid * 1024u;
;     const int aoff = lds_byte(wr * 64 + fr, fq * 8), boff = lds_byte(wc * 32 + fr, fq * 8);
;     ...
;     const char* cA = (const char*)g.A + (size_t)cur.pm * tstepA; const char* cB = (const char*)g.Bt + (size_t)cur.pn * tstepB;
;     PG8_STAGE(PG8_SB(0, 0), cB, voffB); PG8_STAGE(PG8_SB(0, 1), cB + hstepB, voffB); PG8_STAGE(PG8_SA(0, 0), cA, voffA); PG8_STAGE(PG8_SA(0, 1), cA + hstepA, voffA);
;     if (wr == 1) PG8_BAR;
;     PG8_WAIT_V(2); PG8_BAR;
;     PG8_STAGE(PG8_SB(1, 0), cB + kstep, voffB); PG8_STAGE(PG8_SA(1, 0), cA + kstep, voffA); PG8_STAGE(PG8_SB(1, 1), cB + hstepB + kstep, voffB);
;     PG8_WAIT_V(6); PG8_BAR;
.LBB0_92:
	v_readlane_b32 s8, v254, 1
	s_add_i32 s1, s8, -12
	v_readlane_b32 s9, v254, 2
	s_cmp_gt_u32 s1, 11
	v_lshlrev_b32_e32 v19, 6, v15
	s_cselect_b64 s[8:9], -1, 0
	s_cmp_lt_u32 s1, 12
	v_and_b32_e32 v17, 63, v15
	v_and_b32_e32 v18, 48, v15
	v_and_b32_e32 v19, 0x3c0, v19
	v_lshlrev_b32_e32 v15, 2, v15
	s_cselect_b32 s19, s77, 0
	s_cselect_b32 s18, s76, 0
	s_lshl_b32 s1, s11, 13
	v_or_b32_e32 v20, v19, v18
	v_and_b32_e32 v15, 32, v15
	v_bitop3_b32 v20, v20, s1, v15 bitop3:0xde
	s_lshl_b32 s1, s10, 12
	s_add_i32 m0, s41, 0x18000
	v_lshl_add_u64 v[8:9], v[8:9], 0, s[94:95]
	s_and_b32 s1, s1, 0x3000
	global_load_lds_dwordx4 v[8:9], off
	v_lshl_add_u64 v[6:7], v[6:7], 0, s[94:95]
	s_add_i32 m0, s41, 0x1a000
	s_add_i32 s46, s41, 0x8000
	s_add_i32 s47, s41, 0xa000
	global_load_lds_dwordx4 v[6:7], off
	v_lshl_add_u64 v[2:3], v[2:3], 0, s[94:95]
	s_mov_b32 m0, s46
	s_add_u32 s20, s6, 0x40080
	global_load_lds_dwordx4 v[2:3], off
	v_lshl_add_u64 v[2:3], v[4:5], 0, s[94:95]
	s_mov_b32 m0, s47
	s_addc_u32 s21, s7, 0
	global_load_lds_dwordx4 v[2:3], off
	s_add_i32 m0, s41, 0x1c000
	v_lshl_add_u64 v[2:3], s[20:21], 0, v[0:1]
	global_load_lds_dwordx4 v[2:3], off
	v_lshl_add_u64 v[2:3], s[20:21], 0, v[134:135]
	s_add_i32 m0, s41, 0x1e000
	v_and_b32_e32 v4, 1, v10
	global_load_lds_dwordx4 v[2:3], off
	s_waitcnt vmcnt(8)
	s_barrier
	v_lshlrev_b32_e32 v3, 14, v10
	v_and_b32_e32 v3, 0xffff8000, v3
	v_lshl_add_u32 v3, v11, 11, v3
	s_cmpk_lt_u32 s4, 0x100
	v_lshl_or_b32 v3, v4, 6, v3
	s_cselect_b64 s[20:21], -1, 0
	s_lshl_b32 s4, s10, 9
	v_lshl_add_u32 v136, v12, 1, v3
	v_lshlrev_b32_e32 v3, 14, v13
	v_bitop3_b32 v15, v19, v15, v18 bitop3:0x36
	s_cmp_lg_u64 s[18:19], 0
	v_and_b32_e32 v3, 0xffff8000, v3
	v_or_b32_e32 v148, s1, v15
	s_waitcnt vmcnt(6)
	v_readlane_b32 s1, v254, 16
	s_cselect_b64 s[22:23], -1, 0
	s_cmp_lg_u64 s[78:79], 0
	v_lshl_add_u32 v3, v14, 11, v3
	v_and_b32_e32 v4, 1, v13
	v_lshl_add_u32 v2, v17, 2, s1
	v_lshl_or_b32 v149, s11, 6, v17
	s_cselect_b64 s[10:11], -1, 0
	v_lshl_or_b32 v3, v4, 6, v3
	s_mov_b32 s45, 0
	s_and_b64 s[24:25], s[8:9], s[10:11]
	v_mov_b32_e32 v137, v1
	v_lshl_add_u32 v138, v16, 1, v3
	v_mov_b32_e32 v139, v1
	s_mov_b32 s1, -1
	v_add_u32_e32 v150, 0, v20
	v_add_u32_e32 v151, s4, v2
	s_barrier
	s_branch .LBB0_95

; #define PG8_STAGE(bufoff, gbase, voff) do { _Pragma("unroll") for (int _i = 0; _i < 2; ++_i) \
;         __builtin_amdgcn_global_load_lds((const unsigned*)((const char*)(gbase) + (voff)[_i]), (LAS unsigned*)(lds + (bufoff) + ldsw + _i * 8192), 16, 0, 0); } while (0)
; #define PG8_WAIT_V(n) asm volatile("s_waitcnt vmcnt(" #n ")" ::: "memory")
; #define PG8_BAR __builtin_amdgcn_s_barrier()
; template <class Epi, bool ALIGN_EPI>
; __device__ __forceinline__ void gemm_phase(LAS unsigned char* lds, const Gemm g, const StaticOrder& S, const Epi& E) {
;     ...
;     const char* cA = (const char*)g.A + (size_t)cur.pm * tstepA; const char* cB = (const char*)g.Bt + (size_t)cur.pn * tstepB;
;     PG8_STAGE(PG8_SB(0, 0), cB, voffB); PG8_STAGE(PG8_SB(0, 1), cB + hstepB, voffB); PG8_STAGE(PG8_SA(0, 0), cA, voffA); PG8_STAGE(PG8_SA(0, 1), cA + hstepA, voffA);
;     if (wr == 1) PG8_BAR;
;     PG8_WAIT_V(2); PG8_BAR;
;     PG8_STAGE(PG8_SB(1, 0), cB + kstep, voffB); PG8_STAGE(PG8_SA(1, 0), cA + kstep, voffA); PG8_STAGE(PG8_SB(1, 1), cB + hstepB + kstep, voffB);
;     PG8_WAIT_V(6); PG8_BAR;
.LBB0_202:
	v_and_b32_e32 v19, 15, v13
	v_and_b32_e32 v20, 48, v13
	v_lshlrev_b32_e32 v13, 2, v13
	v_lshlrev_b32_e32 v19, 6, v19
	v_and_b32_e32 v13, 32, v13
	s_lshl_b32 s2, s2, 12
	s_add_i32 m0, s29, 0x18000
	v_lshl_add_u64 v[8:9], v[8:9], 0, s[94:95]
	v_or_b32_e32 v21, v19, v20
	s_lshl_b32 s3, s3, 13
	v_bitop3_b32 v19, v19, v13, v20 bitop3:0x36
	s_and_b32 s2, s2, 0x3000
	global_load_lds_dwordx4 v[8:9], off
	v_lshl_add_u64 v[6:7], v[6:7], 0, s[94:95]
	s_add_i32 m0, s29, 0x1a000
	s_add_i32 s35, s29, 0x8000
	s_add_i32 s36, s29, 0xa000
	v_or_b32_e32 v146, s2, v19
	global_load_lds_dwordx4 v[6:7], off
	v_lshl_add_u64 v[2:3], v[2:3], 0, s[94:95]
	s_mov_b32 m0, s35
	s_add_u32 s2, s12, 0xb0080
	v_bitop3_b32 v13, v21, s3, v13 bitop3:0xde
	global_load_lds_dwordx4 v[2:3], off
	v_lshl_add_u64 v[2:3], v[4:5], 0, s[94:95]
	s_mov_b32 m0, s36
	s_addc_u32 s3, s13, 0
	global_load_lds_dwordx4 v[2:3], off
	s_add_i32 m0, s29, 0x1c000
	v_lshl_add_u64 v[2:3], s[2:3], 0, v[0:1]
	global_load_lds_dwordx4 v[2:3], off
	v_lshl_add_u64 v[2:3], s[2:3], 0, v[134:135]
	s_add_i32 m0, s29, 0x1e000
	s_movk_i32 s18, 0xb00
	global_load_lds_dwordx4 v[2:3], off
	s_waitcnt vmcnt(8)
	s_barrier
	v_lshrrev_b32_e32 v3, 1, v10
	v_mul_lo_u32 v2, v12, s18
	s_mov_b32 s19, 0xb000
	s_cmpk_lt_u32 s8, 0x100
	v_mad_u64_u32 v[2:3], s[8:9], v3, s19, v[2:3]
	v_or_b32_e32 v2, v2, v11
	v_add_lshl_u32 v2, v2, v14, 1
	v_mov_b32_e32 v3, v1
	s_mov_b64 s[20:21], 0xb0080
	v_lshl_add_u64 v[136:137], v[2:3], 0, s[20:21]
	v_lshrrev_b32_e32 v3, 1, v15
	v_mul_lo_u32 v2, v17, s18
	v_mad_u64_u32 v[2:3], s[8:9], v3, s19, v[2:3]
	s_waitcnt vmcnt(6)
	v_or_b32_e32 v2, v2, v16
	s_cselect_b64 s[2:3], -1, 0
	s_cmp_lg_u64 s[78:79], 0
	v_add_lshl_u32 v2, v2, v18, 1
	v_mov_b32_e32 v3, v1
	s_cselect_b64 s[16:17], -1, 0
	v_lshl_add_u64 v[138:139], v[2:3], 0, s[20:21]
	s_mov_b32 s37, 0
	v_add_u32_e32 v147, 0, v13
	s_barrier
	s_branch .LBB0_205

; #define PG8_STAGE(bufoff, gbase, voff) do { _Pragma("unroll") for (int _i = 0; _i < 2; ++_i) \
;         __builtin_amdgcn_global_load_lds((const unsigned*)((const char*)(gbase) + (voff)[_i]), (LAS unsigned*)(lds + (bufoff) + ldsw + _i * 8192), 16, 0, 0); } while (0)
; #define PG8_WAIT_V(n) asm volatile("s_waitcnt vmcnt(" #n ")" ::: "memory")
; #define PG8_BAR __builtin_amdgcn_s_barrier()
; template <class Epi, bool ALIGN_EPI>
; __device__ __forceinline__ void gemm_phase(LAS unsigned char* lds, const Gemm g, const StaticOrder& S, const Epi& E) {
;     ...
;     const char* cA = (const char*)g.A + (size_t)cur.pm * tstepA; const char* cB = (const char*)g.Bt + (size_t)cur.pn * tstepB;
;     PG8_STAGE(PG8_SB(0, 0), cB, voffB); PG8_STAGE(PG8_SB(0, 1), cB + hstepB, voffB); PG8_STAGE(PG8_SA(0, 0), cA, voffA); PG8_STAGE(PG8_SA(0, 1), cA + hstepA, voffA);
;     if (wr == 1) PG8_BAR;
;     PG8_WAIT_V(2); PG8_BAR;
;     PG8_STAGE(PG8_SB(1, 0), cB + kstep, voffB); PG8_STAGE(PG8_SA(1, 0), cA + kstep, voffA); PG8_STAGE(PG8_SB(1, 1), cB + hstepB + kstep, voffB);
;     PG8_WAIT_V(6); PG8_BAR;
.LBB0_278:
	v_and_b32_e32 v3, 15, v2
	v_and_b32_e32 v12, 48, v2
	v_lshlrev_b32_e32 v3, 6, v3
	v_lshlrev_b32_e32 v2, 2, v2
	s_sext_i32_i8 s7, s2
	v_or_b32_e32 v13, v3, v12
	s_lshl_b32 s2, s8, 13
	v_and_b32_e32 v2, 32, v2
	v_bitop3_b32 v3, v3, v2, v12 bitop3:0x36
	v_bitop3_b32 v12, v13, s2, v2 bitop3:0xde
	s_lshl_b32 s2, s9, 12
	v_lshl_add_u64 v[4:5], s[22:23], 0, v[0:1]
	v_mov_b32_e32 v135, v1
	s_and_b32 s2, s2, 0x3000
	v_lshl_add_u64 v[6:7], s[22:23], 0, v[134:135]
	v_mov_b32_e32 v131, v1
	v_or_b32_e32 v136, s2, v3
	s_add_i32 m0, s34, 0x18000
	v_lshl_add_u64 v[2:3], v[4:5], 0, s[94:95]
	v_lshl_add_u64 v[8:9], s[20:21], 0, v[130:131]
	v_mov_b32_e32 v133, v1
	global_load_lds_dwordx4 v[2:3], off
	v_lshl_add_u64 v[2:3], v[6:7], 0, s[94:95]
	s_add_i32 m0, s34, 0x1a000
	s_add_i32 s38, s34, 0x8000
	s_add_i32 s39, s34, 0xa000
	v_lshl_add_u64 v[10:11], s[20:21], 0, v[132:133]
	global_load_lds_dwordx4 v[2:3], off
	v_lshl_add_u64 v[2:3], v[8:9], 0, s[94:95]
	s_mov_b32 m0, s38
	s_add_u32 s8, s22, 0x10080
	global_load_lds_dwordx4 v[2:3], off
	v_lshl_add_u64 v[2:3], v[10:11], 0, s[94:95]
	s_mov_b32 m0, s39
	s_addc_u32 s9, s23, 0
	global_load_lds_dwordx4 v[2:3], off
	s_add_i32 m0, s34, 0x1c000
	v_lshl_add_u64 v[2:3], s[8:9], 0, v[0:1]
	global_load_lds_dwordx4 v[2:3], off
	v_lshl_add_u64 v[2:3], s[8:9], 0, v[134:135]
	s_add_i32 m0, s34, 0x1e000
	s_cmpk_lt_u32 s3, 0x100
	global_load_lds_dwordx4 v[2:3], off
	s_waitcnt vmcnt(8)
	s_barrier
	s_waitcnt vmcnt(6)
	v_readlane_b32 s5, v254, 40
	v_readlane_b32 s8, v254, 41
	s_cselect_b64 s[2:3], -1, 0
	s_add_i32 s40, s5, s8
	v_add_u32_e32 v137, 0, v12
	s_barrier
	s_branch .LBB0_281

; #define PG8_STAGE(bufoff, gbase, voff) do { _Pragma("unroll") for (int _i = 0; _i < 2; ++_i) \
;         __builtin_amdgcn_global_load_lds((const unsigned*)((const char*)(gbase) + (voff)[_i]), (LAS unsigned*)(lds + (bufoff) + ldsw + _i * 8192), 16, 0, 0); } while (0)
; #define PG8_WAIT_V(n) asm volatile("s_waitcnt vmcnt(" #n ")" ::: "memory")
; #define PG8_BAR __builtin_amdgcn_s_barrier()
; template <class Epi, bool ALIGN_EPI>
; __device__ __forceinline__ void gemm_phase(LAS unsigned char* lds, const Gemm g, const StaticOrder& S, const Epi& E) {
;     ...
;     const char* cA = (const char*)g.A + (size_t)cur.pm * tstepA; const char* cB = (const char*)g.Bt + (size_t)cur.pn * tstepB;
;     PG8_STAGE(PG8_SB(0, 0), cB, voffB); PG8_STAGE(PG8_SB(0, 1), cB + hstepB, voffB); PG8_STAGE(PG8_SA(0, 0), cA, voffA); PG8_STAGE(PG8_SA(0, 1), cA + hstepA, voffA);
;     if (wr == 1) PG8_BAR;
;     PG8_WAIT_V(2); PG8_BAR;
;     PG8_STAGE(PG8_SB(1, 0), cB + kstep, voffB); PG8_STAGE(PG8_SA(1, 0), cA + kstep, voffA); PG8_STAGE(PG8_SB(1, 1), cB + hstepB + kstep, voffB);
;     PG8_WAIT_V(6); PG8_BAR;
.LBB0_298:
	v_lshlrev_b32_e32 v19, 6, v16
	v_and_b32_e32 v17, 63, v16
	v_and_b32_e32 v18, 48, v16
	v_and_b32_e32 v19, 0x3c0, v19
	v_lshlrev_b32_e32 v16, 2, v16
	s_lshl_b32 s1, s11, 13
	v_or_b32_e32 v20, v19, v18
	v_and_b32_e32 v16, 32, v16
	v_bitop3_b32 v20, v20, s1, v16 bitop3:0xde
	s_lshl_b32 s1, s10, 12
	s_add_i32 m0, s25, 0x18000
	v_lshl_add_u64 v[8:9], v[8:9], 0, s[94:95]
	s_sext_i32_i8 s34, s4
	s_and_b32 s1, s1, 0x3000
	global_load_lds_dwordx4 v[8:9], off
	v_lshl_add_u64 v[6:7], v[6:7], 0, s[94:95]
	s_add_i32 m0, s25, 0x1a000
	s_add_i32 s4, s25, 0x8000
	s_add_i32 s29, s25, 0xa000
	global_load_lds_dwordx4 v[6:7], off
	v_lshl_add_u64 v[2:3], v[2:3], 0, s[94:95]
	s_mov_b32 m0, s4
	s_add_u32 s12, s18, 0x40080
	global_load_lds_dwordx4 v[2:3], off
	v_lshl_add_u64 v[2:3], v[4:5], 0, s[94:95]
	s_mov_b32 m0, s29
	s_addc_u32 s13, s19, 0
	global_load_lds_dwordx4 v[2:3], off
	s_add_i32 m0, s25, 0x1c000
	v_lshl_add_u64 v[2:3], s[12:13], 0, v[0:1]
	global_load_lds_dwordx4 v[2:3], off
	v_lshl_add_u64 v[2:3], s[12:13], 0, v[130:131]
	s_add_i32 m0, s25, 0x1e000
	v_and_b32_e32 v4, 1, v14
	global_load_lds_dwordx4 v[2:3], off
	s_waitcnt vmcnt(8)
	s_barrier
	v_lshlrev_b32_e32 v3, 14, v14
	v_and_b32_e32 v3, 0xffff8000, v3
	v_lshl_add_u32 v3, v13, 11, v3
	v_lshl_or_b32 v3, v4, 6, v3
	v_lshl_add_u32 v136, v15, 1, v3
	v_lshlrev_b32_e32 v3, 14, v10
	v_bitop3_b32 v16, v19, v16, v18 bitop3:0x36
	v_and_b32_e32 v3, 0xffff8000, v3
	v_or_b32_e32 v144, s1, v16
	s_waitcnt vmcnt(6)
	v_readlane_b32 s1, v254, 16
	s_cmpk_lt_u32 s8, 0x100
	v_lshl_add_u32 v3, v11, 11, v3
	v_and_b32_e32 v4, 1, v10
	v_lshl_add_u32 v2, v17, 2, s1
	s_cselect_b64 s[8:9], -1, 0
	s_lshl_b32 s1, s10, 9
	v_lshl_or_b32 v3, v4, 6, v3
	v_lshl_or_b32 v145, s11, 6, v17
	v_mov_b32_e32 v137, v1
	v_lshl_add_u32 v138, v12, 1, v3
	v_mov_b32_e32 v139, v1
	s_mov_b32 s30, 0
	s_mov_b32 s35, -1
	v_add_u32_e32 v146, 0, v20
	v_add_u32_e32 v147, s1, v2
	s_barrier
	s_branch .LBB0_301

; #define PG8_STAGE(bufoff, gbase, voff) do { _Pragma("unroll") for (int _i = 0; _i < 2; ++_i) \
;         __builtin_amdgcn_global_load_lds((const unsigned*)((const char*)(gbase) + (voff)[_i]), (LAS unsigned*)(lds + (bufoff) + ldsw + _i * 8192), 16, 0, 0); } while (0)
; #define PG8_WAIT_V(n) asm volatile("s_waitcnt vmcnt(" #n ")" ::: "memory")
; #define PG8_BAR __builtin_amdgcn_s_barrier()
; template <class Epi, bool ALIGN_EPI>
; __device__ __forceinline__ void gemm_phase(LAS unsigned char* lds, const Gemm g, const StaticOrder& S, const Epi& E) {
;     ...
;     const char* cA = (const char*)g.A + (size_t)cur.pm * tstepA; const char* cB = (const char*)g.Bt + (size_t)cur.pn * tstepB;
;     PG8_STAGE(PG8_SB(0, 0), cB, voffB); PG8_STAGE(PG8_SB(0, 1), cB + hstepB, voffB); PG8_STAGE(PG8_SA(0, 0), cA, voffA); PG8_STAGE(PG8_SA(0, 1), cA + hstepA, voffA);
;     if (wr == 1) PG8_BAR;
;     PG8_WAIT_V(2); PG8_BAR;
;     PG8_STAGE(PG8_SB(1, 0), cB + kstep, voffB); PG8_STAGE(PG8_SA(1, 0), cA + kstep, voffA); PG8_STAGE(PG8_SB(1, 1), cB + hstepB + kstep, voffB);
;     PG8_WAIT_V(6); PG8_BAR;
.LBB0_326:
	v_and_b32_e32 v19, 15, v12
	v_and_b32_e32 v20, 48, v12
	v_lshlrev_b32_e32 v12, 2, v12
	v_lshlrev_b32_e32 v19, 6, v19
	v_and_b32_e32 v12, 32, v12
	s_lshl_b32 s2, s2, 12
	s_add_i32 m0, s29, 0x18000
	v_lshl_add_u64 v[8:9], v[8:9], 0, s[94:95]
	v_or_b32_e32 v21, v19, v20
	s_lshl_b32 s3, s3, 13
	v_bitop3_b32 v19, v19, v12, v20 bitop3:0x36
	s_and_b32 s2, s2, 0x3000
	global_load_lds_dwordx4 v[8:9], off
	v_lshl_add_u64 v[6:7], v[6:7], 0, s[94:95]
	s_add_i32 m0, s29, 0x1a000
	s_add_i32 s35, s29, 0x8000
	s_add_i32 s36, s29, 0xa000
	v_or_b32_e32 v146, s2, v19
	global_load_lds_dwordx4 v[6:7], off
	v_lshl_add_u64 v[2:3], v[2:3], 0, s[94:95]
	s_mov_b32 m0, s35
	s_add_u32 s2, s10, 0x40080
	v_bitop3_b32 v12, v21, s3, v12 bitop3:0xde
	global_load_lds_dwordx4 v[2:3], off
	v_lshl_add_u64 v[2:3], v[4:5], 0, s[94:95]
	s_mov_b32 m0, s36
	s_addc_u32 s3, s11, 0
	global_load_lds_dwordx4 v[2:3], off
	s_add_i32 m0, s29, 0x1c000
	v_lshl_add_u64 v[2:3], s[2:3], 0, v[0:1]
	global_load_lds_dwordx4 v[2:3], off
	v_lshl_add_u64 v[2:3], s[2:3], 0, v[134:135]
	s_add_i32 m0, s29, 0x1e000
	s_movk_i32 s15, 0x1600
	global_load_lds_dwordx4 v[2:3], off
	s_waitcnt vmcnt(8)
	s_barrier
	v_lshrrev_b32_e32 v3, 1, v10
	v_mul_lo_u32 v2, v13, s15
	s_mov_b32 s14, 0x16000
	s_cmpk_lt_u32 s6, 0x100
	v_mad_u64_u32 v[2:3], s[6:7], v3, s14, v[2:3]
	v_or_b32_e32 v2, v2, v11
	v_add_lshl_u32 v2, v2, v14, 1
	v_mov_b32_e32 v3, v1
	s_mov_b64 s[16:17], 0x160080
	v_lshl_add_u64 v[136:137], v[2:3], 0, s[16:17]
	v_lshrrev_b32_e32 v3, 1, v15
	v_mul_lo_u32 v2, v17, s15
	v_mad_u64_u32 v[2:3], s[6:7], v3, s14, v[2:3]
	s_waitcnt vmcnt(6)
	v_or_b32_e32 v2, v2, v16
	s_cselect_b64 s[2:3], -1, 0
	s_cmp_lg_u64 s[78:79], 0
	v_add_lshl_u32 v2, v2, v18, 1
	v_mov_b32_e32 v3, v1
	s_cselect_b64 s[12:13], -1, 0
	v_lshl_add_u64 v[138:139], v[2:3], 0, s[16:17]
	s_mov_b32 s37, 0
	v_add_u32_e32 v147, 0, v12
	s_barrier
	s_branch .LBB0_329

; #define PG8_STAGE(bufoff, gbase, voff) do { _Pragma("unroll") for (int _i = 0; _i < 2; ++_i) \
;         __builtin_amdgcn_global_load_lds((const unsigned*)((const char*)(gbase) + (voff)[_i]), (LAS unsigned*)(lds + (bufoff) + ldsw + _i * 8192), 16, 0, 0); } while (0)
; #define PG8_WAIT_V(n) asm volatile("s_waitcnt vmcnt(" #n ")" ::: "memory")
; #define PG8_BAR __builtin_amdgcn_s_barrier()
; template <class Epi, bool ALIGN_EPI>
; __device__ __forceinline__ void gemm_phase(LAS unsigned char* lds, const Gemm g, const StaticOrder& S, const Epi& E) {
;     ...
;     const char* cA = (const char*)g.A + (size_t)cur.pm * tstepA; const char* cB = (const char*)g.Bt + (size_t)cur.pn * tstepB;
;     PG8_STAGE(PG8_SB(0, 0), cB, voffB); PG8_STAGE(PG8_SB(0, 1), cB + hstepB, voffB); PG8_STAGE(PG8_SA(0, 0), cA, voffA); PG8_STAGE(PG8_SA(0, 1), cA + hstepA, voffA);
;     if (wr == 1) PG8_BAR;
;     PG8_WAIT_V(2); PG8_BAR;
;     PG8_STAGE(PG8_SB(1, 0), cB + kstep, voffB); PG8_STAGE(PG8_SA(1, 0), cA + kstep, voffA); PG8_STAGE(PG8_SB(1, 1), cB + hstepB + kstep, voffB);
;     PG8_WAIT_V(6); PG8_BAR;
.LBB0_402:
	v_and_b32_e32 v19, 15, v18
	v_and_b32_e32 v20, 48, v18
	v_lshlrev_b32_e32 v19, 6, v19
	v_lshlrev_b32_e32 v18, 2, v18
	s_sext_i32_i8 s39, s4
	v_or_b32_e32 v21, v19, v20
	s_lshl_b32 s4, s7, 13
	v_and_b32_e32 v18, 32, v18
	v_bitop3_b32 v19, v19, v18, v20 bitop3:0x36
	v_bitop3_b32 v18, v21, s4, v18 bitop3:0xde
	s_lshl_b32 s4, s12, 12
	s_and_b32 s4, s4, 0x3000
	s_add_i32 m0, s29, 0x18000
	v_lshl_add_u64 v[8:9], v[8:9], 0, s[94:95]
	v_or_b32_e32 v146, s4, v19
	global_load_lds_dwordx4 v[8:9], off
	v_lshl_add_u64 v[6:7], v[6:7], 0, s[94:95]
	s_add_i32 m0, s29, 0x1a000
	s_add_i32 s4, s29, 0x8000
	s_add_i32 s35, s29, 0xa000
	global_load_lds_dwordx4 v[6:7], off
	v_lshl_add_u64 v[2:3], v[2:3], 0, s[94:95]
	s_mov_b32 m0, s4
	s_add_u32 s12, s2, 0x40080
	global_load_lds_dwordx4 v[2:3], off
	v_lshl_add_u64 v[2:3], v[4:5], 0, s[94:95]
	s_mov_b32 m0, s35
	s_addc_u32 s13, s3, 0
	global_load_lds_dwordx4 v[2:3], off
	s_add_i32 m0, s29, 0x1c000
	v_lshl_add_u64 v[2:3], s[12:13], 0, v[0:1]
	global_load_lds_dwordx4 v[2:3], off
	v_lshl_add_u64 v[2:3], s[12:13], 0, v[134:135]
	s_add_i32 m0, s29, 0x1e000
	s_movk_i32 s15, 0x1600
	global_load_lds_dwordx4 v[2:3], off
	s_waitcnt vmcnt(8)
	s_barrier
	v_lshrrev_b32_e32 v3, 1, v10
	v_mul_lo_u32 v2, v12, s15
	s_mov_b32 s14, 0x16000
	s_cmpk_lt_u32 s6, 0x100
	v_mad_u64_u32 v[2:3], s[6:7], v3, s14, v[2:3]
	v_or_b32_e32 v2, v2, v11
	v_add_lshl_u32 v2, v2, v13, 1
	v_mov_b32_e32 v3, v1
	s_mov_b64 s[16:17], 0x160080
	v_lshl_add_u64 v[136:137], v[2:3], 0, s[16:17]
	v_lshrrev_b32_e32 v3, 1, v14
	v_mul_lo_u32 v2, v16, s15
	v_mad_u64_u32 v[2:3], s[6:7], v3, s14, v[2:3]
	s_waitcnt vmcnt(6)
	v_or_b32_e32 v2, v2, v15
	v_add_lshl_u32 v2, v2, v17, 1
	v_mov_b32_e32 v3, v1
	s_cselect_b64 s[12:13], -1, 0
	v_lshl_add_u64 v[138:139], v[2:3], 0, s[16:17]
	s_mov_b32 s36, 0
	v_add_u32_e32 v147, 0, v18
	s_barrier
	s_branch .LBB0_405

; #define PG8_STAGE(bufoff, gbase, voff) do { _Pragma("unroll") for (int _i = 0; _i < 2; ++_i) \
;         __builtin_amdgcn_global_load_lds((const unsigned*)((const char*)(gbase) + (voff)[_i]), (LAS unsigned*)(lds + (bufoff) + ldsw + _i * 8192), 16, 0, 0); } while (0)
; #define PG8_WAIT_V(n) asm volatile("s_waitcnt vmcnt(" #n ")" ::: "memory")
; #define PG8_BAR __builtin_amdgcn_s_barrier()
; template <class Epi, bool ALIGN_EPI>
; __device__ __forceinline__ void gemm_phase(LAS unsigned char* lds, const Gemm g, const StaticOrder& S, const Epi& E) {
;     ...
;     const char* cA = (const char*)g.A + (size_t)cur.pm * tstepA; const char* cB = (const char*)g.Bt + (size_t)cur.pn * tstepB;
;     PG8_STAGE(PG8_SB(0, 0), cB, voffB); PG8_STAGE(PG8_SB(0, 1), cB + hstepB, voffB); PG8_STAGE(PG8_SA(0, 0), cA, voffA); PG8_STAGE(PG8_SA(0, 1), cA + hstepA, voffA);
;     if (wr == 1) PG8_BAR;
;     PG8_WAIT_V(2); PG8_BAR;
;     PG8_STAGE(PG8_SB(1, 0), cB + kstep, voffB); PG8_STAGE(PG8_SA(1, 0), cA + kstep, voffA); PG8_STAGE(PG8_SB(1, 1), cB + hstepB + kstep, voffB);
;     PG8_WAIT_V(6); PG8_BAR;
.LBB0_428:
	v_and_b32_e32 v19, 15, v18
	s_add_u32 s10, s78, 0x3e00800
	v_and_b32_e32 v20, 48, v18
	v_lshlrev_b32_e32 v19, 6, v19
	v_lshlrev_b32_e32 v18, 2, v18
	s_sext_i32_i8 s39, s4
	s_addc_u32 s11, s79, 0
	v_or_b32_e32 v21, v19, v20
	s_lshl_b32 s4, s7, 13
	v_and_b32_e32 v18, 32, v18
	v_bitop3_b32 v19, v19, v18, v20 bitop3:0x36
	v_bitop3_b32 v18, v21, s4, v18 bitop3:0xde
	s_lshl_b32 s4, s12, 12
	s_and_b32 s4, s4, 0x3000
	s_add_i32 m0, s29, 0x18000
	v_lshl_add_u64 v[8:9], v[8:9], 0, s[94:95]
	v_or_b32_e32 v146, s4, v19
	global_load_lds_dwordx4 v[8:9], off
	v_lshl_add_u64 v[6:7], v[6:7], 0, s[94:95]
	s_add_i32 m0, s29, 0x1a000
	s_add_i32 s4, s29, 0x8000
	s_add_i32 s35, s29, 0xa000
	global_load_lds_dwordx4 v[6:7], off
	v_lshl_add_u64 v[2:3], v[2:3], 0, s[94:95]
	s_mov_b32 m0, s4
	s_add_u32 s12, s2, 0x40080
	global_load_lds_dwordx4 v[2:3], off
	v_lshl_add_u64 v[2:3], v[4:5], 0, s[94:95]
	s_mov_b32 m0, s35
	s_addc_u32 s13, s3, 0
	global_load_lds_dwordx4 v[2:3], off
	s_add_i32 m0, s29, 0x1c000
	v_lshl_add_u64 v[2:3], s[12:13], 0, v[0:1]
	global_load_lds_dwordx4 v[2:3], off
	v_lshl_add_u64 v[2:3], s[12:13], 0, v[134:135]
	s_add_i32 m0, s29, 0x1e000
	s_movk_i32 s15, 0x1600
	global_load_lds_dwordx4 v[2:3], off
	s_waitcnt vmcnt(8)
	s_barrier
	v_lshrrev_b32_e32 v3, 1, v10
	v_mul_lo_u32 v2, v12, s15
	s_mov_b32 s14, 0x16000
	s_cmpk_lt_u32 s6, 0x100
	v_mad_u64_u32 v[2:3], s[6:7], v3, s14, v[2:3]
	v_or_b32_e32 v2, v2, v11
	v_add_lshl_u32 v2, v2, v13, 1
	v_mov_b32_e32 v3, v1
	s_mov_b64 s[16:17], 0x160080
	v_lshl_add_u64 v[136:137], v[2:3], 0, s[16:17]
	v_lshrrev_b32_e32 v3, 1, v14
	v_mul_lo_u32 v2, v16, s15
	v_mad_u64_u32 v[2:3], s[6:7], v3, s14, v[2:3]
	s_waitcnt vmcnt(6)
	v_or_b32_e32 v2, v2, v15
	v_add_lshl_u32 v2, v2, v17, 1
	v_mov_b32_e32 v3, v1
	s_cselect_b64 s[12:13], -1, 0
	v_lshl_add_u64 v[138:139], v[2:3], 0, s[16:17]
	s_mov_b32 s36, 0
	v_add_u32_e32 v147, 0, v18
	s_barrier
	s_branch .LBB0_431

; #define PG8_STAGE(bufoff, gbase, voff) do { _Pragma("unroll") for (int _i = 0; _i < 2; ++_i) \
;         __builtin_amdgcn_global_load_lds((const unsigned*)((const char*)(gbase) + (voff)[_i]), (LAS unsigned*)(lds + (bufoff) + ldsw + _i * 8192), 16, 0, 0); } while (0)
; #define PG8_WAIT_V(n) asm volatile("s_waitcnt vmcnt(" #n ")" ::: "memory")
; #define PG8_BAR __builtin_amdgcn_s_barrier()
; template <class Epi, bool ALIGN_EPI>
; __device__ __forceinline__ void gemm_phase(LAS unsigned char* lds, const Gemm g, const StaticOrder& S, const Epi& E) {
;     ...
;     const char* cA = (const char*)g.A + (size_t)cur.pm * tstepA; const char* cB = (const char*)g.Bt + (size_t)cur.pn * tstepB;
;     PG8_STAGE(PG8_SB(0, 0), cB, voffB); PG8_STAGE(PG8_SB(0, 1), cB + hstepB, voffB); PG8_STAGE(PG8_SA(0, 0), cA, voffA); PG8_STAGE(PG8_SA(0, 1), cA + hstepA, voffA);
;     if (wr == 1) PG8_BAR;
;     PG8_WAIT_V(2); PG8_BAR;
;     PG8_STAGE(PG8_SB(1, 0), cB + kstep, voffB); PG8_STAGE(PG8_SA(1, 0), cA + kstep, voffA); PG8_STAGE(PG8_SB(1, 1), cB + hstepB + kstep, voffB);
;     PG8_WAIT_V(6); PG8_BAR;
.LBB0_473:
	v_lshlrev_b32_e32 v19, 6, v16
	v_and_b32_e32 v17, 63, v16
	v_and_b32_e32 v18, 48, v16
	v_and_b32_e32 v19, 0x3c0, v19
	v_lshlrev_b32_e32 v16, 2, v16
	s_lshl_b32 s1, s11, 13
	v_or_b32_e32 v20, v19, v18
	v_and_b32_e32 v16, 32, v16
	v_bitop3_b32 v20, v20, s1, v16 bitop3:0xde
	s_lshl_b32 s1, s10, 12
	s_add_i32 m0, s25, 0x18000
	v_lshl_add_u64 v[8:9], v[8:9], 0, s[94:95]
	s_sext_i32_i8 s34, s4
	s_and_b32 s1, s1, 0x3000
	global_load_lds_dwordx4 v[8:9], off
	v_lshl_add_u64 v[6:7], v[6:7], 0, s[94:95]
	s_add_i32 m0, s25, 0x1a000
	s_add_i32 s4, s25, 0x8000
	s_add_i32 s29, s25, 0xa000
	global_load_lds_dwordx4 v[6:7], off
	v_lshl_add_u64 v[2:3], v[2:3], 0, s[94:95]
	s_mov_b32 m0, s4
	s_add_u32 s12, s18, 0x40080
	global_load_lds_dwordx4 v[2:3], off
	v_lshl_add_u64 v[2:3], v[4:5], 0, s[94:95]
	s_mov_b32 m0, s29
	s_addc_u32 s13, s19, 0
	global_load_lds_dwordx4 v[2:3], off
	s_add_i32 m0, s25, 0x1c000
	v_lshl_add_u64 v[2:3], s[12:13], 0, v[0:1]
	global_load_lds_dwordx4 v[2:3], off
	v_lshl_add_u64 v[2:3], s[12:13], 0, v[134:135]
	s_add_i32 m0, s25, 0x1e000
	v_and_b32_e32 v4, 1, v10
	global_load_lds_dwordx4 v[2:3], off
	s_waitcnt vmcnt(8)
	s_barrier
	v_lshlrev_b32_e32 v3, 14, v10
	v_and_b32_e32 v3, 0xffff8000, v3
	v_lshl_add_u32 v3, v11, 11, v3
	v_lshl_or_b32 v3, v4, 6, v3
	v_lshl_add_u32 v136, v12, 1, v3
	v_lshlrev_b32_e32 v3, 14, v13
	v_bitop3_b32 v16, v19, v16, v18 bitop3:0x36
	v_and_b32_e32 v3, 0xffff8000, v3
	v_or_b32_e32 v140, s1, v16
	s_waitcnt vmcnt(6)
	v_readlane_b32 s1, v254, 16
	s_cmpk_lt_u32 s8, 0x100
	v_lshl_add_u32 v3, v14, 11, v3
	v_and_b32_e32 v4, 1, v13
	v_lshl_add_u32 v2, v17, 2, s1
	s_cselect_b64 s[8:9], -1, 0
	s_lshl_b32 s1, s10, 9
	v_lshl_or_b32 v3, v4, 6, v3
	v_lshl_or_b32 v141, s11, 6, v17
	v_mov_b32_e32 v137, v1
	v_lshl_add_u32 v138, v15, 1, v3
	v_mov_b32_e32 v139, v1
	s_mov_b32 s30, 0
	s_mov_b32 s35, -1
	v_add_u32_e32 v142, 0, v20
	v_add_u32_e32 v143, s1, v2
	s_barrier
	s_branch .LBB0_476

; #define PG8_STAGE(bufoff, gbase, voff) do { _Pragma("unroll") for (int _i = 0; _i < 2; ++_i) \
;         __builtin_amdgcn_global_load_lds((const unsigned*)((const char*)(gbase) + (voff)[_i]), (LAS unsigned*)(lds + (bufoff) + ldsw + _i * 8192), 16, 0, 0); } while (0)
; #define PG8_WAIT_V(n) asm volatile("s_waitcnt vmcnt(" #n ")" ::: "memory")
; #define PG8_BAR __builtin_amdgcn_s_barrier()
; template <class Epi, bool ALIGN_EPI>
; __device__ __forceinline__ void gemm_phase(LAS unsigned char* lds, const Gemm g, const StaticOrder& S, const Epi& E) {
;     ...
;     const char* cA = (const char*)g.A + (size_t)cur.pm * tstepA; const char* cB = (const char*)g.Bt + (size_t)cur.pn * tstepB;
;     PG8_STAGE(PG8_SB(0, 0), cB, voffB); PG8_STAGE(PG8_SB(0, 1), cB + hstepB, voffB); PG8_STAGE(PG8_SA(0, 0), cA, voffA); PG8_STAGE(PG8_SA(0, 1), cA + hstepA, voffA);
;     if (wr == 1) PG8_BAR;
;     PG8_WAIT_V(2); PG8_BAR;
;     PG8_STAGE(PG8_SB(1, 0), cB + kstep, voffB); PG8_STAGE(PG8_SA(1, 0), cA + kstep, voffA); PG8_STAGE(PG8_SB(1, 1), cB + hstepB + kstep, voffB);
;     PG8_WAIT_V(6); PG8_BAR;
.LBB0_597:
	s_add_u32 s2, s78, 0x3b00000
	s_addc_u32 s3, s79, 0
	v_lshlrev_b32_e32 v18, 6, v15
	s_add_u32 s10, s78, 0x1ee00000
	v_and_b32_e32 v16, 63, v15
	v_and_b32_e32 v17, 48, v15
	v_and_b32_e32 v18, 0x3c0, v18
	v_lshlrev_b32_e32 v15, 2, v15
	s_addc_u32 s11, s79, 0
	s_lshl_b32 s9, s15, 13
	v_or_b32_e32 v19, v18, v17
	v_and_b32_e32 v15, 32, v15
	v_bitop3_b32 v19, v19, s9, v15 bitop3:0xde
	s_lshl_b32 s9, s14, 12
	s_add_i32 m0, s30, 0x18000
	v_lshl_add_u64 v[8:9], v[8:9], 0, s[94:95]
	s_and_b32 s9, s9, 0x3000
	global_load_lds_dwordx4 v[8:9], off
	v_lshl_add_u64 v[6:7], v[6:7], 0, s[94:95]
	s_add_i32 m0, s30, 0x1a000
	s_add_i32 s36, s30, 0x8000
	s_add_i32 s37, s30, 0xa000
	global_load_lds_dwordx4 v[6:7], off
	v_lshl_add_u64 v[2:3], v[2:3], 0, s[94:95]
	s_mov_b32 m0, s36
	s_add_u32 s16, s24, 0x40080
	global_load_lds_dwordx4 v[2:3], off
	v_lshl_add_u64 v[2:3], v[4:5], 0, s[94:95]
	s_mov_b32 m0, s37
	s_addc_u32 s17, s25, 0
	global_load_lds_dwordx4 v[2:3], off
	s_add_i32 m0, s30, 0x1c000
	v_lshl_add_u64 v[2:3], s[16:17], 0, v[132:133]
	global_load_lds_dwordx4 v[2:3], off
	v_lshl_add_u64 v[2:3], s[16:17], 0, v[136:137]
	s_add_i32 m0, s30, 0x1e000
	v_bitop3_b32 v15, v18, v15, v17 bitop3:0x36
	global_load_lds_dwordx4 v[2:3], off
	s_waitcnt vmcnt(8)
	s_barrier
	v_lshlrev_b32_e32 v3, 14, v0
	v_and_b32_e32 v3, 0xffff8000, v3
	v_lshl_add_u32 v3, v10, 11, v3
	v_and_b32_e32 v0, 1, v0
	v_lshl_or_b32 v0, v0, 6, v3
	v_lshl_add_u32 v138, v11, 1, v0
	v_lshlrev_b32_e32 v0, 14, v12
	v_and_b32_e32 v0, 0xffff8000, v0
	v_or_b32_e32 v158, s9, v15
	s_waitcnt vmcnt(6)
	v_readlane_b32 s9, v254, 16
	s_cmpk_lt_u32 s12, 0x100
	v_lshl_add_u32 v0, v13, 11, v0
	v_and_b32_e32 v3, 1, v12
	v_lshl_add_u32 v2, v16, 2, s9
	s_cselect_b64 s[12:13], -1, 0
	s_lshl_b32 s9, s14, 9
	v_lshl_or_b32 v0, v3, 6, v0
	v_lshl_or_b32 v159, s15, 6, v16
	v_mov_b32_e32 v139, v1
	v_lshl_add_u32 v140, v14, 1, v0
	v_mov_b32_e32 v141, v1
	s_mov_b32 s38, 0
	s_mov_b32 s23, -1
	v_add_u32_e32 v160, 0, v19
	v_add_u32_e32 v161, s9, v2
	s_barrier
	s_branch .LBB0_600

; #define PG8_STAGE(bufoff, gbase, voff) do { _Pragma("unroll") for (int _i = 0; _i < 2; ++_i) \
;         __builtin_amdgcn_global_load_lds((const unsigned*)((const char*)(gbase) + (voff)[_i]), (LAS unsigned*)(lds + (bufoff) + ldsw + _i * 8192), 16, 0, 0); } while (0)
; #define PG8_WAIT_V(n) asm volatile("s_waitcnt vmcnt(" #n ")" ::: "memory")
; #define PG8_BAR __builtin_amdgcn_s_barrier()
; template <class Epi, bool ALIGN_EPI>
; __device__ __forceinline__ void gemm_phase(LAS unsigned char* lds, const Gemm g, const StaticOrder& S, const Epi& E) {
;     ...
;     const char* cA = (const char*)g.A + (size_t)cur.pm * tstepA; const char* cB = (const char*)g.Bt + (size_t)cur.pn * tstepB;
;     PG8_STAGE(PG8_SB(0, 0), cB, voffB); PG8_STAGE(PG8_SB(0, 1), cB + hstepB, voffB); PG8_STAGE(PG8_SA(0, 0), cA, voffA); PG8_STAGE(PG8_SA(0, 1), cA + hstepA, voffA);
;     if (wr == 1) PG8_BAR;
;     PG8_WAIT_V(2); PG8_BAR;
;     PG8_STAGE(PG8_SB(1, 0), cB + kstep, voffB); PG8_STAGE(PG8_SA(1, 0), cA + kstep, voffA); PG8_STAGE(PG8_SB(1, 1), cB + hstepB + kstep, voffB);
;     PG8_WAIT_V(6); PG8_BAR;
.LBB0_705:
	v_and_b32_e32 v19, 15, v14
	v_and_b32_e32 v20, 48, v14
	v_lshlrev_b32_e32 v14, 2, v14
	v_lshlrev_b32_e32 v19, 6, v19
	v_and_b32_e32 v14, 32, v14
	s_lshl_b32 s6, s6, 12
	s_add_i32 m0, s35, 0x18000
	v_lshl_add_u64 v[8:9], v[8:9], 0, s[94:95]
	v_or_b32_e32 v21, v19, v20
	s_lshl_b32 s7, s7, 13
	v_bitop3_b32 v19, v19, v14, v20 bitop3:0x36
	s_and_b32 s6, s6, 0x3000
	global_load_lds_dwordx4 v[8:9], off
	v_lshl_add_u64 v[6:7], v[6:7], 0, s[94:95]
	s_add_i32 m0, s35, 0x1a000
	s_add_i32 s39, s35, 0x8000
	s_add_i32 s40, s35, 0xa000
	v_or_b32_e32 v160, s6, v19
	global_load_lds_dwordx4 v[6:7], off
	v_lshl_add_u64 v[2:3], v[2:3], 0, s[94:95]
	s_mov_b32 m0, s39
	s_add_u32 s6, s10, 0xb0080
	v_bitop3_b32 v14, v21, s7, v14 bitop3:0xde
	global_load_lds_dwordx4 v[2:3], off
	v_lshl_add_u64 v[2:3], v[4:5], 0, s[94:95]
	s_mov_b32 m0, s40
	s_addc_u32 s7, s11, 0
	global_load_lds_dwordx4 v[2:3], off
	s_add_i32 m0, s35, 0x1c000
	v_lshl_add_u64 v[2:3], s[6:7], 0, v[0:1]
	global_load_lds_dwordx4 v[2:3], off
	v_lshl_add_u64 v[2:3], s[6:7], 0, v[142:143]
	s_add_i32 m0, s35, 0x1e000
	s_cmpk_lt_u32 s12, 0x100
	global_load_lds_dwordx4 v[2:3], off
	s_waitcnt vmcnt(8)
	s_barrier
	s_movk_i32 s12, 0xb00
	v_lshrrev_b32_e32 v3, 1, v10
	v_mul_lo_u32 v2, v12, s12
	s_mov_b32 s13, 0xb000
	v_mad_u64_u32 v[2:3], s[6:7], v3, s13, v[2:3]
	v_or_b32_e32 v2, v2, v11
	v_add_lshl_u32 v2, v2, v13, 1
	v_mov_b32_e32 v3, v1
	s_mov_b64 s[22:23], 0xb0080
	v_lshl_add_u64 v[144:145], v[2:3], 0, s[22:23]
	v_lshrrev_b32_e32 v3, 1, v15
	v_mul_lo_u32 v2, v17, s12
	v_mad_u64_u32 v[2:3], s[6:7], v3, s13, v[2:3]
	s_waitcnt vmcnt(6)
	s_cselect_b64 s[16:17], -1, 0
	s_cmp_lg_u64 s[0:1], 0
	v_or_b32_e32 v2, v2, v16
	s_cselect_b64 s[18:19], -1, 0
	s_cmp_lg_u64 s[78:79], 0
	v_add_lshl_u32 v2, v2, v18, 1
	v_mov_b32_e32 v3, v1
	s_cselect_b64 s[20:21], -1, 0
	v_lshl_add_u64 v[146:147], v[2:3], 0, s[22:23]
	s_mov_b32 s41, 0
	v_add_u32_e32 v161, 0, v14
	s_barrier
	s_branch .LBB0_708

; #define PG8_STAGE(bufoff, gbase, voff) do { _Pragma("unroll") for (int _i = 0; _i < 2; ++_i) \
;         __builtin_amdgcn_global_load_lds((const unsigned*)((const char*)(gbase) + (voff)[_i]), (LAS unsigned*)(lds + (bufoff) + ldsw + _i * 8192), 16, 0, 0); } while (0)
; #define PG8_WAIT_V(n) asm volatile("s_waitcnt vmcnt(" #n ")" ::: "memory")
; #define PG8_BAR __builtin_amdgcn_s_barrier()
; template <class Epi, bool ALIGN_EPI>
; __device__ __forceinline__ void gemm_phase(LAS unsigned char* lds, const Gemm g, const StaticOrder& S, const Epi& E) {
;     ...
;     const char* cA = (const char*)g.A + (size_t)cur.pm * tstepA; const char* cB = (const char*)g.Bt + (size_t)cur.pn * tstepB;
;     PG8_STAGE(PG8_SB(0, 0), cB, voffB); PG8_STAGE(PG8_SB(0, 1), cB + hstepB, voffB); PG8_STAGE(PG8_SA(0, 0), cA, voffA); PG8_STAGE(PG8_SA(0, 1), cA + hstepA, voffA);
;     if (wr == 1) PG8_BAR;
;     PG8_WAIT_V(2); PG8_BAR;
;     PG8_STAGE(PG8_SB(1, 0), cB + kstep, voffB); PG8_STAGE(PG8_SA(1, 0), cA + kstep, voffA); PG8_STAGE(PG8_SB(1, 1), cB + hstepB + kstep, voffB);
;     PG8_WAIT_V(6); PG8_BAR;
.LBB0_843:
	s_lshl_b32 s9, s10, 12
	s_add_i32 m0, s23, 0x18000
	v_lshl_add_u64 v[8:9], v[8:9], 0, s[94:95]
	s_lshl_b32 s1, s11, 13
	s_and_b32 s9, s9, 0x3000
	global_load_lds_dwordx4 v[8:9], off
	v_lshl_add_u64 v[6:7], v[6:7], 0, s[94:95]
	s_add_i32 m0, s23, 0x1a000
	s_add_i32 s27, s23, 0x8000
	s_add_i32 s28, s23, 0xa000
	global_load_lds_dwordx4 v[6:7], off
	v_lshl_add_u64 v[2:3], v[2:3], 0, s[94:95]
	s_mov_b32 m0, s27
	s_add_u32 s12, s18, 0x40080
	global_load_lds_dwordx4 v[2:3], off
	v_lshl_add_u64 v[2:3], v[4:5], 0, s[94:95]
	s_mov_b32 m0, s28
	s_addc_u32 s13, s19, 0
	global_load_lds_dwordx4 v[2:3], off
	s_add_i32 m0, s23, 0x1c000
	v_lshl_add_u64 v[2:3], s[12:13], 0, v[0:1]
	global_load_lds_dwordx4 v[2:3], off
	v_lshl_add_u64 v[2:3], s[12:13], 0, v[130:131]
	s_add_i32 m0, s23, 0x1e000
	v_lshlrev_b32_e32 v4, 6, v11
	global_load_lds_dwordx4 v[2:3], off
	s_waitcnt vmcnt(8)
	s_barrier
	v_and_b32_e32 v3, 48, v11
	v_and_b32_e32 v4, 0x3c0, v4
	v_lshlrev_b32_e32 v6, 2, v11
	v_or_b32_e32 v5, v4, v3
	v_and_b32_e32 v6, 32, v6
	v_and_b32_e32 v2, 63, v11
	v_bitop3_b32 v5, v5, s1, v6 bitop3:0xde
	v_bitop3_b32 v3, v4, v6, v3 bitop3:0x36
	v_readlane_b32 s1, v254, 16
	v_or_b32_e32 v144, s9, v3
	v_lshl_or_b32 v145, s11, 6, v2
	v_lshl_add_u32 v3, v2, 2, s1
	v_lshlrev_b32_e32 v2, 14, v15
	v_and_b32_e32 v2, 0xffff8000, v2
	v_lshl_add_u32 v2, v14, 11, v2
	v_and_b32_e32 v4, 1, v15
	v_lshl_or_b32 v2, v4, 6, v2
	v_lshl_add_u32 v136, v16, 1, v2
	v_lshlrev_b32_e32 v2, 14, v10
	v_and_b32_e32 v2, 0xffff8000, v2
	s_waitcnt vmcnt(6)
	s_cmpk_lt_u32 s8, 0x100
	v_lshl_add_u32 v2, v12, 11, v2
	v_and_b32_e32 v4, 1, v10
	s_cselect_b64 s[8:9], -1, 0
	s_lshl_b32 s1, s10, 9
	v_lshl_or_b32 v2, v4, 6, v2
	s_sext_i32_i8 s30, s4
	v_mov_b32_e32 v137, v1
	v_lshl_add_u32 v138, v13, 1, v2
	v_mov_b32_e32 v139, v1
	s_mov_b32 s4, 0
	s_mov_b32 s31, -1
	v_add_u32_e32 v146, 0, v5
	v_add_u32_e32 v147, s1, v3
	s_barrier
	s_branch .LBB0_846
